# attention: next-round V prefetch moved from the load-bound first segment to the end of the round (after the stores, before the end barrier)
# baseline (speedup 1.0000x reference)
; __device__ __forceinline__ AttnItem attn_item(int it) {
;     AttnItem a; a.head = it / 768; const int pb = it - a.head * 768, gi = a.head >> 2; a.dsh = gi * 2;
;     const int p0 = pb * 64; int lsh; if (p0 < 32768) { a.seq_base = p0 & ~8191; lsh = 13; } else { a.seq_base = 32768; lsh = 14; }
;     const int lm = lsh - a.dsh; a.m = 1 << lm; const int local = p0 - a.seq_base; a.r = local >> lm; a.i0 = local - (a.r << lm);
;     a.pos0 = a.seq_base + (a.i0 << a.dsh); return a;
; }
; __device__ __forceinline__ int attn_pair(int j, int c, int G) {
;     if ((G & 7) == 0 && (4608 % G) == 0) { const int per_xcd = 4608 / 8, wpx = G >> 3; return (c & 7) * per_xcd + j * wpx + (c >> 3); }
;     return j * G + c;
; }
; __device__ __forceinline__ void attn_load_v(const AttnItem& a, const bf16_t* qkv, int ht, u32x4 (&vreg)[12]) {
; #pragma unroll
;     for (int pass = 0; pass < 12; ++pass) {
;         const int row = pass * 16 + (ht >> 4), ch = ht & 15, ki = a.i0 - 64 + row;
;         u32x4 val = (u32x4){0u, 0u, 0u, 0u};
;         if (ki >= 0 && ki < a.m) val = *(const u32x4*)(qkv + ((size_t)(24 + a.head) * M_TOK + a.seq_base + a.r * a.m + ki) * 128 + ch * 8);
;         vreg[pass] = val;
;     }
; }
; __device__ __forceinline__ void attn_phase(LAS unsigned char* lds, bf16_t* qkv, float* lse, const float* biasT, int G) {
;     ...
;         if (pairn < 4608) { const AttnItem an = attn_item(pairn * 2 + half); attn_load_v(an, qkv, ht, vreg); }
.LBB0_412:
	s_or_b64 exec, exec, s[0:1]
	v_readlane_b32 s14, v253, 0
	s_cmpk_gt_i32 s14, 0x11ff
	s_cbranch_scc1 .Lattn_v_done
	s_lshl_b32 s0, s14, 1
	s_add_i32 s0, s0, s94
	s_mul_hi_i32 s1, s0, 0x2aaaaaab
	s_lshr_b32 s14, s1, 31
	s_ashr_i32 s1, s1, 7
	s_add_i32 s14, s1, s14
	s_mul_i32 s1, s14, 0xfffffd00
	s_add_i32 s1, s1, s0
	s_lshl_b32 s0, s1, 6
	s_and_b32 s16, s0, 0xffffe000
	s_cmpk_lt_i32 s1, 0x200
	s_cselect_b32 s1, 13, 14
	s_cselect_b32 s16, s16, 0x8000
	s_ashr_i32 s17, s14, 1
	s_and_b32 s17, s17, -2
	s_sub_i32 s1, s1, s17
	s_lshl_b32 s18, 1, s1
	s_sub_i32 s0, s0, s16
	s_lshl_b32 s1, -1, s1
	s_and_b32 s17, s1, s0
	s_sub_i32 s19, s0, s17
	s_cmp_lt_i32 s19, 64
	s_cbranch_scc1 .Lattn_vslow
	s_add_i32 s0, s19, 0x80
	s_cmp_gt_i32 s0, s18
	s_cbranch_scc1 .Lattn_vslow
	s_add_i32 s28, s14, 24
	s_mul_i32 s28, s28, 0xc000
	s_add_i32 s28, s28, s16
	s_add_i32 s28, s28, s17
	s_add_i32 s28, s28, s19
	v_add_u32_e32 v0, s28, v220
	v_lshlrev_b32_e32 v0, 8, v0
	s_mov_b64 s[28:29], 0x1000
	v_lshl_add_u64 v[2:3], v[188:189], 0, v[0:1]
	v_lshl_add_u64 v[2:3], s[28:29], 0, v[2:3]
	s_mov_b64 s[28:29], 0x2000
	global_load_dwordx4 v[8:11], v[2:3], off offset:-4096
	global_load_dwordx4 v[4:7], v[2:3], off
	v_lshl_add_u64 v[2:3], s[28:29], 0, v[2:3]
	global_load_dwordx4 v[12:15], v[2:3], off offset:-4096
	global_load_dwordx4 v[16:19], v[2:3], off
	v_lshl_add_u64 v[2:3], s[28:29], 0, v[2:3]
	global_load_dwordx4 v[20:23], v[2:3], off offset:-4096
	global_load_dwordx4 v[24:27], v[2:3], off
	v_lshl_add_u64 v[2:3], s[28:29], 0, v[2:3]
	global_load_dwordx4 v[28:31], v[2:3], off offset:-4096
	global_load_dwordx4 v[32:35], v[2:3], off
	v_lshl_add_u64 v[2:3], s[28:29], 0, v[2:3]
	global_load_dwordx4 v[36:39], v[2:3], off offset:-4096
	global_load_dwordx4 v[40:43], v[2:3], off
	v_lshl_add_u64 v[2:3], s[28:29], 0, v[2:3]
	global_load_dwordx4 v[44:47], v[2:3], off offset:-4096
	global_load_dwordx4 v[48:51], v[2:3], off
	s_branch .Lattn_v_done

; __device__ __forceinline__ void attn_phase(LAS unsigned char* lds, bf16_t* qkv, float* lse, const float* biasT, int G) {
;     ...
;     for (int j = 0; j < nrounds; ++j) {
;         const int pair = attn_pair(j, cwg, G); if (pair >= 4608) break;
;         const int pairn = (j + 1 < nrounds) ? attn_pair(j + 1, cwg, G) : 4608;
;     ...
;         __syncthreads();
.Lattn_v_done:
	v_readlane_b32 s0, v251, 30
	s_add_i32 s10, s97, s0
	v_readlane_b32 s0, v251, 11
	s_cmp_eq_u32 s0, s8
	s_cselect_b64 s[0:1], -1, 0
	s_barrier

; #define LAS __attribute__((address_space(3)))
; #define ATT_LOADK(buf, grp) do { _Pragma("unroll") for (int tt = 0; tt < 3; ++tt) { int ki = kbase + 16 * ((grp) * 3 + tt); ki = ki < 0 ? 0 : (ki > a.m - 1 ? a.m - 1 : ki); \
;             const bf16_t* kp = kcol + (size_t)ki * 128; \
;             _Pragma("unroll") for (int ks = 0; ks < 4; ++ks) Kf[buf][tt][ks] = *(const bf16x8*)(kp + 32 * ks); } } while (0)
; #define ATT_MMAK(buf, grp) do { _Pragma("unroll") for (int tt = 0; tt < 3; ++tt) { f32x4 acc_ = (f32x4){0.f, 0.f, 0.f, 0.f}; \
;             _Pragma("unroll") for (int ks = 0; ks < 4; ++ks) acc_ = __builtin_amdgcn_mfma_f32_16x16x32_bf16(Kf[buf][tt][ks], Qf[ks], acc_, 0, 0, 0); sa[(grp) * 3 + tt] = acc_; } } while (0)
; __device__ __forceinline__ void attn_phase(LAS unsigned char* lds, bf16_t* qkv, float* lse, const float* biasT, int G) {
;     ...
;         const AttnItem a = attn_item(pair * 2 + half);
; #pragma unroll
;         for (int pass = 0; pass < 12; ++pass) *(LAS u32x4*)(vs + (pass * 16 + (ht >> 4)) * VS_PITCH + (ht & 15) * 16) = vreg[pass];
;         if (ht < 129) bs[16 + ht] = biasT[a.head * 132 + ht];
;         __syncthreads();
;         const size_t tokq = (size_t)(a.pos0 + a.r + ((16 * w4 + li) << a.dsh));
;         const int pbase = a.seq_base + a.r * a.m;
;         bf16_t* qp = qkv + ((size_t)a.head * M_TOK + pbase + a.i0 + 16 * w4 + li) * 128;
;         bf16x8 Qf[4];
; #pragma unroll
;         for (int ks = 0; ks < 4; ++ks) Qf[ks] = *(const bf16x8*)(qp + 32 * ks + 8 * lg);
;         const int kbase = a.i0 - 64 + 16 * w4 + li;
;         const bf16_t* kcol = qkv + ((size_t)(12 + a.head) * M_TOK + pbase) * 128 + 8 * lg;
;         f32x4 sa[10];
;         bf16x8 Kf[2][3][4];
;     ...
;         ATT_LOADK(0, 0); ATT_LOADK(1, 1);
;         __builtin_amdgcn_sched_barrier(0);
;         ATT_MMAK(0, 0);
;         __builtin_amdgcn_sched_barrier(0);
;         ATT_LOADK(0, 2);
.LBB0_425:
	s_or_b64 exec, exec, s[0:1]
	s_mul_i32 s0, s10, 0xfffffd00
	s_add_i32 s0, s0, s9
	s_lshl_b32 s1, s0, 6
	s_and_b32 s9, s1, 0xffffe000
	s_cmpk_lt_i32 s0, 0x200
	s_cselect_b32 s0, 13, 14
	s_cselect_b32 s9, s9, 0x8000
	s_ashr_i32 s11, s10, 1
	s_and_b32 s12, s11, -2
	s_sub_i32 s11, s0, s12
	s_sub_i32 s30, s1, s9
	s_ashr_i32 s96, s30, s11
	s_lshl_b32 s31, s96, s11
	s_sub_i32 s13, s30, s31
	s_add_i32 s16, s31, s9
	s_mul_hi_i32 s0, s10, 0xc000
	s_ashr_i32 s18, s16, 31
	s_ashr_i32 s1, s13, 31
	s_mul_i32 s17, s10, 0xc000
	v_mov_b32_e32 v3, s0
	s_add_u32 s0, s13, s16
	v_or_b32_e32 v2, s17, v184
	s_addc_u32 s1, s1, s18
	v_lshl_add_u64 v[2:3], s[0:1], 0, v[2:3]
	v_readlane_b32 s0, v250, 21
	s_add_i32 s15, s13, s0
	s_add_i32 s0, s10, 12
	s_add_i32 s17, s17, 0x90000
	v_lshlrev_b64 v[2:3], 8, v[2:3]
	s_mul_hi_i32 s1, s0, 0xc000
	s_add_u32 s0, s17, s16
	v_lshl_add_u64 v[194:195], s[92:93], 0, v[2:3]
	v_mov_b32_e32 v191, v1
	s_addc_u32 s1, s1, s18
	v_lshl_add_u64 v[2:3], v[194:195], 0, v[190:191]
	s_lshl_b64 s[0:1], s[0:1], 8
	global_load_dwordx4 v[96:99], v[2:3], off
	global_load_dwordx4 v[92:95], v[2:3], off offset:64
	global_load_dwordx4 v[88:91], v[2:3], off offset:128
	global_load_dwordx4 v[52:55], v[2:3], off offset:192
	v_add_u32_e32 v0, s15, v216
	v_lshl_add_u64 v[2:3], v[186:187], 0, s[0:1]
	s_bfm_b32 s0, s11, 0
	v_min_i32_e32 v56, s0, v0
	v_ashrrev_i32_e32 v57, 31, v56
	v_lshlrev_b64 v[56:57], 7, v[56:57]
	v_cmp_lt_i32_e32 vcc, -1, v0
	s_movk_i32 s1, 0xffef
	v_add_u32_e32 v58, 48, v0
	v_cndmask_b32_e32 v57, 0, v57, vcc
	v_cndmask_b32_e32 v56, 0, v56, vcc
	v_lshl_add_u64 v[56:57], v[56:57], 1, v[2:3]
	global_load_dwordx4 v[68:71], v[56:57], off
	global_load_dwordx4 v[72:75], v[56:57], off offset:64
	global_load_dwordx4 v[80:83], v[56:57], off offset:128
	global_load_dwordx4 v[84:87], v[56:57], off offset:192
	v_add_u32_e32 v56, 16, v0
	v_min_i32_e32 v56, s0, v56
	v_ashrrev_i32_e32 v57, 31, v56
	v_lshlrev_b64 v[56:57], 7, v[56:57]
	v_cmp_lt_i32_e32 vcc, s1, v0
	s_movk_i32 s1, 0xffdf
	v_add_u32_e32 v102, 64, v0
	v_cndmask_b32_e32 v57, 0, v57, vcc
	v_cndmask_b32_e32 v56, 0, v56, vcc
	v_lshl_add_u64 v[56:57], v[56:57], 1, v[2:3]
	global_load_dwordx4 v[116:119], v[56:57], off
	global_load_dwordx4 v[136:139], v[56:57], off offset:64
	global_load_dwordx4 v[140:143], v[56:57], off offset:128
	global_load_dwordx4 v[144:147], v[56:57], off offset:192
	v_add_u32_e32 v56, 32, v0
	v_min_i32_e32 v56, s0, v56
	v_ashrrev_i32_e32 v57, 31, v56
	v_lshlrev_b64 v[56:57], 7, v[56:57]
	v_cmp_lt_i32_e32 vcc, s1, v0
	v_min_i32_e32 v100, s0, v102
	v_add_u32_e32 v122, 0x50, v0
	v_cndmask_b32_e32 v57, 0, v57, vcc
	v_cndmask_b32_e32 v56, 0, v56, vcc
	v_lshl_add_u64 v[56:57], v[56:57], 1, v[2:3]
	global_load_dwordx4 v[148:151], v[56:57], off
	global_load_dwordx4 v[152:155], v[56:57], off offset:64
	global_load_dwordx4 v[156:159], v[56:57], off offset:128
	global_load_dwordx4 v[160:163], v[56:57], off offset:192
	v_min_i32_e32 v56, s0, v58
	v_ashrrev_i32_e32 v57, 31, v56
	v_lshlrev_b64 v[56:57], 7, v[56:57]
	v_cmp_lt_i32_e32 vcc, -1, v58
	v_ashrrev_i32_e32 v101, 31, v100
	v_min_i32_e32 v120, s0, v122
	v_cndmask_b32_e32 v57, 0, v57, vcc
	v_cndmask_b32_e32 v56, 0, v56, vcc
	v_lshlrev_b64 v[100:101], 7, v[100:101]
	v_cmp_lt_i32_e32 vcc, -1, v102
	v_ashrrev_i32_e32 v121, 31, v120
	v_lshlrev_b64 v[120:121], 7, v[120:121]
	v_cndmask_b32_e32 v101, 0, v101, vcc
	v_cndmask_b32_e32 v100, 0, v100, vcc
	v_cmp_lt_i32_e32 vcc, -1, v122
	v_lshl_add_u64 v[76:77], v[56:57], 1, v[2:3]
	v_lshl_add_u64 v[112:113], v[100:101], 1, v[2:3]
	v_cndmask_b32_e32 v121, 0, v121, vcc
	v_cndmask_b32_e32 v120, 0, v120, vcc
	v_lshl_add_u64 v[132:133], v[120:121], 1, v[2:3]
	global_load_dwordx4 v[56:59], v[76:77], off
	global_load_dwordx4 v[60:63], v[76:77], off offset:64
	global_load_dwordx4 v[64:67], v[76:77], off offset:128
	s_nop 0
	global_load_dwordx4 v[76:79], v[76:77], off offset:192
	s_nop 0
	global_load_dwordx4 v[100:103], v[112:113], off
	global_load_dwordx4 v[104:107], v[112:113], off offset:64
	global_load_dwordx4 v[108:111], v[112:113], off offset:128
	s_nop 0
	global_load_dwordx4 v[112:115], v[112:113], off offset:192
	s_nop 0
	global_load_dwordx4 v[120:123], v[132:133], off
	global_load_dwordx4 v[124:127], v[132:133], off offset:64
	global_load_dwordx4 v[128:131], v[132:133], off offset:128
	s_nop 0
	global_load_dwordx4 v[132:135], v[132:133], off offset:192
	s_waitcnt vmcnt(23)
	v_mfma_f32_16x16x32_bf16 v[68:71], v[68:71], v[96:99], 0
	s_waitcnt vmcnt(22)
	v_mfma_f32_16x16x32_bf16 v[68:71], v[72:75], v[92:95], v[68:71]
	s_waitcnt vmcnt(21)
	v_mfma_f32_16x16x32_bf16 v[68:71], v[80:83], v[88:91], v[68:71]
	s_waitcnt vmcnt(20)
	v_mfma_f32_16x16x32_bf16 v[84:87], v[84:87], v[52:55], v[68:71]
	s_waitcnt vmcnt(19)
	v_mfma_f32_16x16x32_bf16 v[68:71], v[116:119], v[96:99], 0
	s_waitcnt vmcnt(18)
	v_mfma_f32_16x16x32_bf16 v[68:71], v[136:139], v[92:95], v[68:71]
	s_waitcnt vmcnt(17)
	v_mfma_f32_16x16x32_bf16 v[68:71], v[140:143], v[88:91], v[68:71]
	s_waitcnt vmcnt(16)
	v_mfma_f32_16x16x32_bf16 v[72:75], v[144:147], v[52:55], v[68:71]
	s_waitcnt vmcnt(15)
	v_mfma_f32_16x16x32_bf16 v[68:71], v[148:151], v[96:99], 0
	s_waitcnt vmcnt(14)
	v_mfma_f32_16x16x32_bf16 v[68:71], v[152:155], v[92:95], v[68:71]
	s_waitcnt vmcnt(13)
	v_mfma_f32_16x16x32_bf16 v[68:71], v[156:159], v[88:91], v[68:71]
	s_waitcnt vmcnt(12)
	v_mfma_f32_16x16x32_bf16 v[68:71], v[160:163], v[52:55], v[68:71]
	v_add_u32_e32 v82, 0x60, v0
	v_min_i32_e32 v80, s0, v82
	v_ashrrev_i32_e32 v81, 31, v80
	v_lshlrev_b64 v[80:81], 7, v[80:81]
	v_cmp_lt_i32_e32 vcc, -1, v82
	v_add_u32_e32 v82, 0x70, v0
	v_add_u32_e32 v0, 0x80, v0
	v_cndmask_b32_e32 v81, 0, v81, vcc
	v_cndmask_b32_e32 v80, 0, v80, vcc
	v_lshl_add_u64 v[80:81], v[80:81], 1, v[2:3]
	global_load_dwordx4 v[136:139], v[80:81], off
	global_load_dwordx4 v[140:143], v[80:81], off offset:64
	global_load_dwordx4 v[144:147], v[80:81], off offset:128
	global_load_dwordx4 v[148:151], v[80:81], off offset:192
	v_min_i32_e32 v80, s0, v82
	v_ashrrev_i32_e32 v81, 31, v80
	v_lshlrev_b64 v[80:81], 7, v[80:81]
	v_cmp_lt_i32_e32 vcc, -1, v82
	s_cmpk_gt_i32 s14, 0x11ff
	s_nop 0
	v_cndmask_b32_e32 v81, 0, v81, vcc
	v_cndmask_b32_e32 v80, 0, v80, vcc
	v_lshl_add_u64 v[80:81], v[80:81], 1, v[2:3]
	global_load_dwordx4 v[152:155], v[80:81], off
	global_load_dwordx4 v[156:159], v[80:81], off offset:64
	global_load_dwordx4 v[160:163], v[80:81], off offset:128
	global_load_dwordx4 v[164:167], v[80:81], off offset:192
	v_min_i32_e32 v80, s0, v0
	v_ashrrev_i32_e32 v81, 31, v80
	v_lshlrev_b64 v[80:81], 7, v[80:81]
	v_cmp_lt_i32_e32 vcc, -1, v0
	s_nop 1
	v_cndmask_b32_e32 v81, 0, v81, vcc
	v_cndmask_b32_e32 v80, 0, v80, vcc
	v_lshl_add_u64 v[2:3], v[80:81], 1, v[2:3]
	global_load_dwordx4 v[176:179], v[2:3], off
	global_load_dwordx4 v[172:175], v[2:3], off offset:64
	global_load_dwordx4 v[168:171], v[2:3], off offset:128
	global_load_dwordx4 v[116:119], v[2:3], off offset:192
	v_writelane_b32 v253, s14, 0

; template <bool COOP>
; __global__ void __launch_bounds__(512, 2) fwd_kernel(Params p) {
;     ...
;     }
; }
.LBB0_641:
	s_nop 0
	s_nop 0
	s_nop 0
	s_nop 0
	s_nop 0
	s_nop 0
	s_nop 0
	s_nop 0
	s_nop 0
	s_nop 0
	s_nop 0
	s_nop 0
	s_nop 0
	s_nop 0
	s_nop 0
	s_nop 0
	s_nop 0
	s_nop 0
	s_nop 0
	s_nop 0
	s_nop 0
	s_nop 0
	s_nop 0
	s_nop 0
	s_nop 0
	s_nop 0
	s_nop 0
	s_nop 0
	s_nop 0
	s_nop 0
	s_nop 0
	s_nop 0
	s_nop 0
	s_nop 0
	s_nop 0
	s_nop 0
	s_nop 0
	s_nop 0
	s_nop 0
	s_nop 0
	s_nop 0
	s_nop 0
	s_nop 0
	s_nop 0
	s_nop 0
	s_nop 0
	s_nop 0
	s_nop 0
	s_nop 0
	s_nop 0
	s_nop 0
	s_nop 0
	s_nop 0
	s_nop 0
	s_nop 0
	s_nop 0
	s_nop 0
	s_nop 0
	s_nop 0
	s_nop 0
	s_nop 0
	s_nop 0
	s_nop 0
	s_nop 0
	s_nop 0
	s_nop 0
	s_nop 0
	s_nop 0
	s_nop 0
	s_nop 0
	s_nop 0
	s_nop 0
	s_nop 0
	s_nop 0
	s_nop 0
	s_nop 0
	s_nop 0
	s_nop 0
	s_nop 0
	s_nop 0
	s_nop 0
	s_nop 0
	s_nop 0
	s_nop 0
	s_nop 0
	s_nop 0
	s_nop 0
	s_nop 0
	s_nop 0
	s_nop 0
	s_nop 0
	s_nop 0
	s_nop 0
	s_nop 0
	s_nop 0
	s_nop 0
	s_nop 0
	s_nop 0
	s_nop 0
	s_nop 0
	s_nop 0
	s_nop 0
	s_nop 0
	s_nop 0
	s_nop 0
	s_nop 0
	s_nop 0
	s_nop 0
	s_nop 0
	s_nop 0
	s_nop 0
	s_nop 0
	s_nop 0
	s_nop 0
	s_nop 0
	s_nop 0
	s_nop 0
	s_nop 0
	s_nop 0
	s_nop 0
	s_nop 0
	s_nop 0
	s_nop 0
	s_nop 0
	s_nop 0
	s_nop 0
	s_nop 0
	s_nop 0
	s_nop 0
	s_nop 0
	s_nop 0
	s_nop 0
	s_nop 0
	s_nop 0
	s_nop 0
	s_nop 0
	s_nop 0
	s_nop 0
	s_nop 0
	s_nop 0
	s_nop 0
	s_nop 0
	s_nop 0
	s_nop 0
	s_nop 0
	s_nop 0
	s_nop 0
	s_nop 0
	s_nop 0
	s_nop 0
	s_nop 0
	s_nop 0
	s_nop 0
	s_nop 0
	s_nop 0
	s_nop 0
	s_nop 0
	s_nop 0
	s_nop 0
	s_nop 0
	s_nop 0
	s_nop 0
	s_nop 0
	s_nop 0
	s_nop 0
	s_nop 0
	s_nop 0
	s_nop 0
	s_nop 0
	s_nop 0
	s_nop 0
	s_nop 0
	s_nop 0
	s_nop 0
	s_nop 0
	s_nop 0
	s_nop 0
	s_nop 0
	s_nop 0
	s_nop 0
	s_nop 0
	s_nop 0
	s_nop 0
	s_nop 0
	s_nop 0
	s_nop 0
	s_nop 0
	s_nop 0
	s_nop 0
	s_nop 0
	s_nop 0
	s_nop 0
	s_nop 0
	s_nop 0
	s_nop 0
	s_nop 0
	s_nop 0
	s_nop 0
	s_nop 0
	s_nop 0
	s_nop 0
	s_nop 0
	s_nop 0
	s_nop 0
	s_nop 0
	s_nop 0
	s_nop 0
	s_nop 0
	s_nop 0
	s_nop 0
	s_nop 0
	s_nop 0
	s_nop 0
	s_nop 0
	s_nop 0
	s_nop 0
	s_nop 0
	s_nop 0
	s_nop 0
	s_nop 0
	s_nop 0
	s_nop 0
	s_nop 0
	s_nop 0
	s_nop 0
	s_nop 0
	s_nop 0
	s_nop 0
	s_nop 0
	s_nop 0
	s_nop 0
	s_nop 0
	s_nop 0
	s_nop 0
	s_nop 0
	s_nop 0
	s_nop 0
	s_nop 0
	s_nop 0
	s_nop 0
	s_nop 0
	s_nop 0
	s_nop 0
	s_nop 0
	s_nop 0
	s_nop 0
	s_nop 0
	s_nop 0
	s_nop 0
	s_nop 0
	s_nop 0
	s_nop 0
	s_nop 0
	s_nop 0
	s_nop 0
	s_nop 0
	s_nop 0
	s_nop 0
	s_nop 0
	s_nop 0
	s_nop 0
	s_nop 0
	s_nop 0
	s_nop 0
	s_nop 0
	s_nop 0
	s_nop 0
	s_nop 0
	s_nop 0
	s_nop 0
	s_nop 0
	s_nop 0
	s_nop 0
	s_nop 0
	s_nop 0
	s_nop 0
	s_nop 0
	s_nop 0
	s_nop 0
	s_nop 0
	s_nop 0
	s_nop 0
	s_nop 0
	s_nop 0
	s_nop 0
	s_nop 0
	s_nop 0
	s_nop 0
	s_nop 0
	s_nop 0
	s_nop 0
	s_nop 0
	s_endpgm
